# row-norm passes: shift/scale modulation vector loads issued up front (one wait) in the initial and mid-layer LN passes
# speedup vs baseline: 1.0022x; 1.0022x over previous
.LBB0_288:
	v_mov_b32_e32 v0, v36
	v_readlane_b32 s26, v255, 3
	v_lshlrev_b32_e32 v32, 2, v0
	v_ashrrev_i32_e32 v33, 31, v32
	v_lshlrev_b64 v[34:35], 2, v[32:33]
	v_lshl_add_u64 v[0:1], s[4:5], 0, v[34:35]
	global_load_dwordx4 v[28:31], v[0:1], off
	global_load_dwordx4 v[24:27], v[0:1], off offset:1024
	global_load_dwordx4 v[20:23], v[0:1], off offset:2048
	global_load_dwordx4 v[16:19], v[0:1], off offset:3072
	v_add_co_u32_e32 v40, vcc, s28, v0
	s_min_i32 s4, s14, 0x4000
	s_nop 0
	v_addc_co_u32_e32 v41, vcc, 0, v1, vcc
	global_load_dwordx4 v[12:15], v[40:41], off
	global_load_dwordx4 v[8:11], v[40:41], off offset:1024
	global_load_dwordx4 v[4:7], v[40:41], off offset:2048
	global_load_dwordx4 v[0:3], v[40:41], off offset:3072
	s_ashr_i32 s4, s4, 12
	s_mul_hi_i32 s5, s4, 0xc000
	s_mul_i32 s4, s4, 0xc000
	v_readlane_b32 s27, v255, 4
	s_add_u32 s4, s26, s4
	s_addc_u32 s5, s27, s5
	s_waitcnt vmcnt(7)
	v_add_f32_e32 v39, v28, v29
	v_add_f32_e32 v40, v30, v31
	s_waitcnt vmcnt(6)
	v_add_f32_e32 v41, v24, v25
	v_add_f32_e32 v42, v26, v27
	v_add_f32_e32 v39, v39, v40
	s_waitcnt vmcnt(5)
	v_add_f32_e32 v43, v20, v21
	v_add_f32_e32 v44, v22, v23
	v_add_f32_e32 v40, v41, v42
	v_add_f32_e32 v39, 0, v39
	s_waitcnt vmcnt(4)
	v_add_f32_e32 v45, v16, v17
	v_add_f32_e32 v46, v18, v19
	v_add_f32_e32 v41, v43, v44
	v_add_f32_e32 v39, v40, v39
	v_add_f32_e32 v42, v45, v46
	s_waitcnt vmcnt(3)
	v_add_f32_e32 v43, v12, v13
	v_add_f32_e32 v44, v14, v15
	v_add_f32_e32 v39, v41, v39
	s_waitcnt vmcnt(2)
	v_add_f32_e32 v45, v8, v9
	v_add_f32_e32 v46, v10, v11
	v_add_f32_e32 v43, v43, v44
	v_add_f32_e32 v39, v42, v39
	s_waitcnt vmcnt(1)
	v_add_f32_e32 v47, v4, v5
	v_add_f32_e32 v48, v6, v7
	v_add_f32_e32 v44, v45, v46
	v_add_f32_e32 v39, v43, v39
	s_waitcnt vmcnt(0)
	v_add_f32_e32 v49, v0, v1
	v_add_f32_e32 v50, v2, v3
	v_add_f32_e32 v45, v47, v48
	v_add_f32_e32 v39, v44, v39
	v_add_f32_e32 v46, v49, v50
	v_add_f32_e32 v39, v45, v39
	v_add_f32_e32 v39, v46, v39
	ds_swizzle_b32 v40, v39 offset:swizzle(SWAP,1)
	s_waitcnt lgkmcnt(0)
	v_add_f32_e32 v39, v39, v40
	ds_swizzle_b32 v40, v39 offset:swizzle(SWAP,2)
	s_waitcnt lgkmcnt(0)
	v_add_f32_e32 v39, v39, v40
	ds_swizzle_b32 v40, v39 offset:swizzle(SWAP,4)
	s_waitcnt lgkmcnt(0)
	v_add_f32_e32 v39, v39, v40
	ds_swizzle_b32 v40, v39 offset:swizzle(SWAP,8)
	s_waitcnt lgkmcnt(0)
	v_add_f32_e32 v39, v39, v40
	ds_swizzle_b32 v40, v39 offset:swizzle(SWAP,16)
	s_waitcnt lgkmcnt(0)
	v_add_f32_e32 v39, v39, v40
	v_mov_b32_e32 v40, v39
	s_nop 1
	v_permlane32_swap_b32_e32 v39, v40
	v_add_f32_e32 v39, v39, v40
	v_fmamk_f32 v31, v39, 0xba000000, v31
	v_fmac_f32_e32 v29, 0xba000000, v39
	v_fmamk_f32 v27, v39, 0xba000000, v27
	v_fmac_f32_e32 v25, 0xba000000, v39
	v_fmamk_f32 v30, v39, 0xba000000, v30
	v_fmamk_f32 v28, v39, 0xba000000, v28
	v_fmamk_f32 v26, v39, 0xba000000, v26
	v_fmamk_f32 v24, v39, 0xba000000, v24
	v_fmamk_f32 v23, v39, 0xba000000, v23
	v_fmac_f32_e32 v21, 0xba000000, v39
	v_mul_f32_e32 v40, v29, v29
	v_mul_f32_e32 v41, v31, v31
	v_mul_f32_e32 v42, v25, v25
	v_mul_f32_e32 v43, v27, v27
	v_fmamk_f32 v22, v39, 0xba000000, v22
	v_fmamk_f32 v20, v39, 0xba000000, v20
	v_fmamk_f32 v19, v39, 0xba000000, v19
	v_fmac_f32_e32 v17, 0xba000000, v39
	v_mul_f32_e32 v44, v21, v21
	v_mul_f32_e32 v45, v23, v23
	v_fmac_f32_e32 v40, v28, v28
	v_fmac_f32_e32 v41, v30, v30
	v_fmac_f32_e32 v42, v24, v24
	v_fmac_f32_e32 v43, v26, v26
	v_fmamk_f32 v18, v39, 0xba000000, v18
	v_fmamk_f32 v16, v39, 0xba000000, v16
	v_fmamk_f32 v15, v39, 0xba000000, v15
	v_fmac_f32_e32 v13, 0xba000000, v39
	v_mul_f32_e32 v46, v17, v17
	v_mul_f32_e32 v47, v19, v19
	v_fmac_f32_e32 v44, v20, v20
	v_fmac_f32_e32 v45, v22, v22
	v_add_f32_e32 v40, v40, v41
	v_add_f32_e32 v41, v42, v43
	v_fmamk_f32 v14, v39, 0xba000000, v14
	v_fmamk_f32 v12, v39, 0xba000000, v12
	v_fmamk_f32 v11, v39, 0xba000000, v11
	v_fmac_f32_e32 v9, 0xba000000, v39
	v_mul_f32_e32 v48, v13, v13
	v_mul_f32_e32 v49, v15, v15
	v_fmac_f32_e32 v46, v16, v16
	v_fmac_f32_e32 v47, v18, v18
	v_add_f32_e32 v42, v44, v45
	v_add_f32_e32 v40, v40, v41
	v_fmamk_f32 v10, v39, 0xba000000, v10
	v_fmamk_f32 v8, v39, 0xba000000, v8
	v_fmamk_f32 v7, v39, 0xba000000, v7
	v_fmac_f32_e32 v5, 0xba000000, v39
	v_mul_f32_e32 v50, v9, v9
	v_mul_f32_e32 v51, v11, v11
	v_fmac_f32_e32 v48, v12, v12
	v_fmac_f32_e32 v49, v14, v14
	v_add_f32_e32 v43, v46, v47
	v_add_f32_e32 v40, v42, v40
	v_fmamk_f32 v6, v39, 0xba000000, v6
	v_fmamk_f32 v4, v39, 0xba000000, v4
	v_mul_f32_e32 v52, v5, v5
	v_mul_f32_e32 v53, v7, v7
	v_fmac_f32_e32 v50, v8, v8
	v_fmac_f32_e32 v51, v10, v10
	v_add_f32_e32 v44, v48, v49
	v_add_f32_e32 v40, v43, v40
	v_lshl_add_u64 v[48:49], s[4:5], 0, v[34:35]
	v_fmac_f32_e32 v52, v4, v4
	v_fmac_f32_e32 v53, v6, v6
	v_add_f32_e32 v45, v50, v51
	v_add_f32_e32 v40, v44, v40
	v_add_co_u32_e32 v50, vcc, s30, v48
	v_add_f32_e32 v46, v52, v53
	v_add_f32_e32 v40, v45, v40
	v_addc_co_u32_e32 v51, vcc, 0, v49, vcc
	v_add_f32_e32 v52, v46, v40
	global_load_dwordx4 v[40:43], v[50:51], off offset:-4096
	global_load_dwordx4 v[44:47], v[48:49], off
	v_add_co_u32_e32 v246, vcc, s28, v48
	s_nop 1
	v_addc_co_u32_e32 v247, vcc, 0, v49, vcc
	global_load_dwordx4 v[190:193], v[50:51], off offset:-3072
	global_load_dwordx4 v[194:197], v[48:49], off offset:1024
	global_load_dwordx4 v[198:201], v[50:51], off offset:-2048
	global_load_dwordx4 v[202:205], v[48:49], off offset:2048
	global_load_dwordx4 v[206:209], v[50:51], off offset:-1024
	global_load_dwordx4 v[210:213], v[48:49], off offset:3072
	global_load_dwordx4 v[214:217], v[50:51], off offset:0
	global_load_dwordx4 v[218:221], v[246:247], off
	global_load_dwordx4 v[222:225], v[50:51], off offset:1024
	global_load_dwordx4 v[226:229], v[246:247], off offset:1024
	global_load_dwordx4 v[230:233], v[50:51], off offset:2048
	global_load_dwordx4 v[234:237], v[246:247], off offset:2048
	global_load_dwordx4 v[238:241], v[50:51], off offset:3072
	global_load_dwordx4 v[242:245], v[246:247], off offset:3072
	v_fmamk_f32 v3, v39, 0xba000000, v3
	v_fmac_f32_e32 v1, 0xba000000, v39
	v_fmamk_f32 v2, v39, 0xba000000, v2
	v_fmamk_f32 v0, v39, 0xba000000, v0
	v_mul_f32_e32 v39, v1, v1
	v_mul_f32_e32 v53, v3, v3
	v_fmac_f32_e32 v39, v0, v0
	v_fmac_f32_e32 v53, v2, v2
	v_add_f32_e32 v34, v39, v53
	v_add_f32_e32 v34, v34, v52
	ds_swizzle_b32 v35, v34 offset:swizzle(SWAP,1)
	s_waitcnt lgkmcnt(0)
	v_add_f32_e32 v34, v34, v35
	ds_swizzle_b32 v35, v34 offset:swizzle(SWAP,2)
	s_waitcnt lgkmcnt(0)
	v_add_f32_e32 v34, v34, v35
	ds_swizzle_b32 v35, v34 offset:swizzle(SWAP,4)
	s_waitcnt lgkmcnt(0)
	v_add_f32_e32 v34, v34, v35
	ds_swizzle_b32 v35, v34 offset:swizzle(SWAP,8)
	s_waitcnt lgkmcnt(0)
	v_add_f32_e32 v34, v34, v35
	ds_swizzle_b32 v35, v34 offset:swizzle(SWAP,16)
	s_waitcnt lgkmcnt(0)
	v_add_f32_e32 v34, v34, v35
	v_mov_b32_e32 v35, v34
	s_nop 1
	v_permlane32_swap_b32_e32 v34, v35
	v_add_f32_e32 v34, v34, v35
	v_fmamk_f32 v34, v34, 0x3a000000, v37
	v_mul_f32_e32 v35, 0x4f800000, v34
	v_cmp_gt_f32_e32 vcc, s29, v34
	s_nop 1
	v_cndmask_b32_e32 v34, v34, v35, vcc
	v_sqrt_f32_e32 v35, v34
	s_nop 0
	v_add_u32_e32 v39, -1, v35
	v_add_u32_e32 v52, 1, v35
	v_fma_f32 v53, -v39, v35, v34
	v_fma_f32 v54, -v52, v35, v34
	v_cmp_ge_f32_e64 s[4:5], 0, v53
	s_nop 1
	v_cndmask_b32_e64 v35, v35, v39, s[4:5]
	v_cmp_lt_f32_e64 s[4:5], 0, v54
	s_nop 1
	v_cndmask_b32_e64 v35, v35, v52, s[4:5]
	v_mul_f32_e32 v39, 0x37800000, v35
	v_cndmask_b32_e32 v35, v35, v39, vcc
	v_cmp_class_f32_e32 vcc, v34, v38
	s_nop 1
	v_cndmask_b32_e32 v34, v35, v34, vcc
	v_div_scale_f32 v35, s[4:5], v34, v34, 1.0
	v_rcp_f32_e32 v39, v35
	s_lshl_b64 s[4:5], s[20:21], 12
	s_add_u32 s4, s96, s4
	s_addc_u32 s5, s97, s5
	v_fma_f32 v52, -v35, v39, 1.0
	v_fmac_f32_e32 v39, v52, v39
	v_div_scale_f32 v52, vcc, 1.0, v34, 1.0
	v_mul_f32_e32 v53, v52, v39
	v_fma_f32 v54, -v35, v53, v52
	v_fmac_f32_e32 v53, v54, v39
	v_fma_f32 v35, -v35, v53, v52
	v_div_fmas_f32 v35, v35, v39, v53
	v_div_fixup_f32 v52, v35, v34, 1.0
	v_lshl_add_u64 v[56:57], v[32:33], 1, s[4:5]
	v_pk_mul_f32 v[28:29], v[28:29], v[52:53] op_sel_hi:[1,0]
	v_pk_mul_f32 v[30:31], v[30:31], v[52:53] op_sel_hi:[1,0]
	s_waitcnt vmcnt(1)
	v_pk_add_f32 v[32:33], v[42:43], 1.0 op_sel_hi:[1,0]
	v_pk_add_f32 v[34:35], v[40:41], 1.0 op_sel_hi:[1,0]
	s_waitcnt vmcnt(0)
	v_pk_fma_f32 v[30:31], v[32:33], v[30:31], v[46:47]
	v_pk_fma_f32 v[28:29], v[34:35], v[28:29], v[44:45]
	v_lshl_add_u64 v[54:55], v[48:49], 0, s[12:13]
	v_cvt_pk_bf16_f32 v28, v28, v29
	v_cvt_pk_bf16_f32 v29, v30, v31
	global_store_dwordx2 v[56:57], v[28:29], off
	v_pk_mul_f32 v[24:25], v[24:25], v[52:53] op_sel_hi:[1,0]
	v_pk_mul_f32 v[26:27], v[26:27], v[52:53] op_sel_hi:[1,0]
	v_pk_mul_f32 v[20:21], v[20:21], v[52:53] op_sel_hi:[1,0]
	v_pk_mul_f32 v[22:23], v[22:23], v[52:53] op_sel_hi:[1,0]
	v_pk_mul_f32 v[16:17], v[16:17], v[52:53] op_sel_hi:[1,0]
	v_pk_mul_f32 v[18:19], v[18:19], v[52:53] op_sel_hi:[1,0]
	v_pk_mul_f32 v[12:13], v[12:13], v[52:53] op_sel_hi:[1,0]
	v_pk_mul_f32 v[14:15], v[14:15], v[52:53] op_sel_hi:[1,0]
	v_pk_mul_f32 v[8:9], v[8:9], v[52:53] op_sel_hi:[1,0]
	v_pk_mul_f32 v[10:11], v[10:11], v[52:53] op_sel_hi:[1,0]
	v_pk_mul_f32 v[4:5], v[4:5], v[52:53] op_sel_hi:[1,0]
	v_pk_mul_f32 v[6:7], v[6:7], v[52:53] op_sel_hi:[1,0]
	v_pk_mul_f32 v[0:1], v[0:1], v[52:53] op_sel_hi:[1,0]
	v_pk_mul_f32 v[2:3], v[2:3], v[52:53] op_sel_hi:[1,0]
	s_add_u32 s14, s14, s92
	s_addc_u32 s15, s15, s93
	s_add_u32 s6, s6, s8
	s_addc_u32 s7, s7, s9
	s_cmpk_gt_i32 s14, 0x43ff
	v_pk_add_f32 v[192:193], v[192:193], 1.0 op_sel_hi:[1,0]
	v_pk_add_f32 v[190:191], v[190:191], 1.0 op_sel_hi:[1,0]
	v_pk_fma_f32 v[26:27], v[192:193], v[26:27], v[196:197]
	v_pk_fma_f32 v[24:25], v[190:191], v[24:25], v[194:195]
	s_nop 0
	v_cvt_pk_bf16_f32 v24, v24, v25
	v_cvt_pk_bf16_f32 v25, v26, v27
	global_store_dwordx2 v[56:57], v[24:25], off offset:512
	v_pk_add_f32 v[200:201], v[200:201], 1.0 op_sel_hi:[1,0]
	v_pk_add_f32 v[198:199], v[198:199], 1.0 op_sel_hi:[1,0]
	v_pk_fma_f32 v[22:23], v[200:201], v[22:23], v[204:205]
	v_pk_fma_f32 v[20:21], v[198:199], v[20:21], v[202:203]
	s_nop 0
	v_cvt_pk_bf16_f32 v20, v20, v21
	v_cvt_pk_bf16_f32 v21, v22, v23
	global_store_dwordx2 v[56:57], v[20:21], off offset:1024
	v_pk_add_f32 v[208:209], v[208:209], 1.0 op_sel_hi:[1,0]
	v_pk_add_f32 v[206:207], v[206:207], 1.0 op_sel_hi:[1,0]
	v_pk_fma_f32 v[18:19], v[208:209], v[18:19], v[212:213]
	v_pk_fma_f32 v[16:17], v[206:207], v[16:17], v[210:211]
	s_nop 0
	v_cvt_pk_bf16_f32 v16, v16, v17
	v_cvt_pk_bf16_f32 v17, v18, v19
	global_store_dwordx2 v[56:57], v[16:17], off offset:1536
	v_pk_add_f32 v[216:217], v[216:217], 1.0 op_sel_hi:[1,0]
	v_pk_add_f32 v[214:215], v[214:215], 1.0 op_sel_hi:[1,0]
	v_pk_fma_f32 v[14:15], v[216:217], v[14:15], v[220:221]
	v_pk_fma_f32 v[12:13], v[214:215], v[12:13], v[218:219]
	s_nop 0
	v_cvt_pk_bf16_f32 v12, v12, v13
	v_cvt_pk_bf16_f32 v13, v14, v15
	global_store_dwordx2 v[56:57], v[12:13], off offset:2048
	v_pk_add_f32 v[224:225], v[224:225], 1.0 op_sel_hi:[1,0]
	v_pk_add_f32 v[222:223], v[222:223], 1.0 op_sel_hi:[1,0]
	v_pk_fma_f32 v[10:11], v[224:225], v[10:11], v[228:229]
	v_pk_fma_f32 v[8:9], v[222:223], v[8:9], v[226:227]
	s_nop 0
	v_cvt_pk_bf16_f32 v8, v8, v9
	v_cvt_pk_bf16_f32 v9, v10, v11
	global_store_dwordx2 v[56:57], v[8:9], off offset:2560
	v_pk_add_f32 v[232:233], v[232:233], 1.0 op_sel_hi:[1,0]
	v_pk_add_f32 v[230:231], v[230:231], 1.0 op_sel_hi:[1,0]
	v_pk_fma_f32 v[6:7], v[232:233], v[6:7], v[236:237]
	v_pk_fma_f32 v[4:5], v[230:231], v[4:5], v[234:235]
	s_nop 0
	v_cvt_pk_bf16_f32 v4, v4, v5
	v_cvt_pk_bf16_f32 v5, v6, v7
	global_store_dwordx2 v[56:57], v[4:5], off offset:3072
	v_pk_add_f32 v[240:241], v[240:241], 1.0 op_sel_hi:[1,0]
	v_pk_add_f32 v[238:239], v[238:239], 1.0 op_sel_hi:[1,0]
	v_pk_fma_f32 v[2:3], v[240:241], v[2:3], v[244:245]
	v_pk_fma_f32 v[0:1], v[238:239], v[0:1], v[242:243]
	s_nop 0
	v_cvt_pk_bf16_f32 v0, v0, v1
	v_cvt_pk_bf16_f32 v1, v2, v3
	global_store_dwordx2 v[56:57], v[0:1], off offset:3584
	s_cbranch_scc1 .LBB0_293

.LBB0_1548:
	s_waitcnt vmcnt(7)
	v_add_f32_e32 v0, v30, v31
	v_add_f32_e32 v36, v32, v33
	v_add_f32_e32 v0, v0, v36
	s_waitcnt vmcnt(6)
	v_add_f32_e32 v36, v26, v27
	v_add_f32_e32 v37, v28, v29
	v_add_f32_e32 v0, 0, v0
	v_add_f32_e32 v36, v36, v37
	v_add_f32_e32 v0, v36, v0
	s_waitcnt vmcnt(5)
	v_add_f32_e32 v36, v22, v23
	v_add_f32_e32 v37, v24, v25
	v_add_f32_e32 v36, v36, v37
	v_add_f32_e32 v0, v36, v0
	s_waitcnt vmcnt(4)
	v_add_f32_e32 v36, v18, v19
	v_add_f32_e32 v37, v20, v21
	v_add_f32_e32 v36, v36, v37
	v_add_f32_e32 v0, v36, v0
	s_waitcnt vmcnt(3)
	v_add_f32_e32 v36, v14, v15
	v_add_f32_e32 v37, v16, v17
	v_add_f32_e32 v36, v36, v37
	v_add_f32_e32 v0, v36, v0
	s_waitcnt vmcnt(2)
	v_add_f32_e32 v36, v10, v11
	v_add_f32_e32 v37, v12, v13
	v_add_f32_e32 v36, v36, v37
	v_add_f32_e32 v0, v36, v0
	s_waitcnt vmcnt(1)
	v_add_f32_e32 v36, v6, v7
	v_add_f32_e32 v37, v8, v9
	v_add_f32_e32 v36, v36, v37
	v_add_f32_e32 v0, v36, v0
	s_waitcnt vmcnt(0)
	v_add_f32_e32 v36, v2, v3
	v_add_f32_e32 v37, v4, v5
	v_add_f32_e32 v36, v36, v37
	v_add_f32_e32 v0, v36, v0
	ds_swizzle_b32 v36, v0 offset:swizzle(SWAP,1)
	s_min_i32 s4, s10, 0x4000
	s_ashr_i32 s4, s4, 12
	s_mul_hi_i32 s5, s4, 0xc000
	s_mul_i32 s4, s4, 0xc000
	s_waitcnt lgkmcnt(0)
	v_add_f32_e32 v0, v0, v36
	ds_swizzle_b32 v36, v0 offset:swizzle(SWAP,2)
	s_add_u32 s4, s22, s4
	s_addc_u32 s5, s23, s5
	v_lshl_add_u64 v[44:45], v[34:35], 2, s[4:5]
	s_mov_b32 s4, 0x9000
	s_waitcnt lgkmcnt(0)
	v_add_f32_e32 v0, v0, v36
	ds_swizzle_b32 v36, v0 offset:swizzle(SWAP,4)
	v_add_co_u32_e32 v46, vcc, s4, v44
	s_movk_i32 s4, 0x7000
	s_nop 0
	v_addc_co_u32_e32 v47, vcc, 0, v45, vcc
	s_waitcnt lgkmcnt(0)
	v_add_f32_e32 v0, v0, v36
	ds_swizzle_b32 v36, v0 offset:swizzle(SWAP,8)
	v_add_co_u32_e32 v48, vcc, s4, v44
	s_add_u32 s10, s10, s92
	s_nop 0
	v_addc_co_u32_e32 v49, vcc, 0, v45, vcc
	s_waitcnt lgkmcnt(0)
	v_add_f32_e32 v0, v0, v36
	ds_swizzle_b32 v36, v0 offset:swizzle(SWAP,16)
	s_addc_u32 s11, s11, s93
	global_load_dwordx4 v[40:43], v[48:49], off offset:-4096
	s_waitcnt lgkmcnt(0)
	v_add_f32_e32 v0, v0, v36
	v_mov_b32_e32 v36, v0
	s_nop 1
	v_permlane32_swap_b32_e32 v0, v36
	v_add_f32_e32 v0, v0, v36
	v_fmac_f32_e32 v33, 0xba000000, v0
	v_fmac_f32_e32 v31, 0xba000000, v0
	v_fmac_f32_e32 v32, 0xba000000, v0
	v_fmac_f32_e32 v30, 0xba000000, v0
	v_mul_f32_e32 v36, v31, v31
	v_mul_f32_e32 v37, v33, v33
	v_fmac_f32_e32 v36, v30, v30
	v_fmac_f32_e32 v37, v32, v32
	v_fmac_f32_e32 v29, 0xba000000, v0
	v_fmac_f32_e32 v27, 0xba000000, v0
	v_add_f32_e32 v36, v36, v37
	v_fmac_f32_e32 v28, 0xba000000, v0
	v_fmac_f32_e32 v26, 0xba000000, v0
	v_mul_f32_e32 v37, v27, v27
	v_mul_f32_e32 v38, v29, v29
	v_fmac_f32_e32 v37, v26, v26
	v_fmac_f32_e32 v38, v28, v28
	v_add_f32_e32 v37, v37, v38
	v_fmac_f32_e32 v25, 0xba000000, v0
	v_fmac_f32_e32 v23, 0xba000000, v0
	v_add_f32_e32 v36, v36, v37
	v_fmac_f32_e32 v24, 0xba000000, v0
	v_fmac_f32_e32 v22, 0xba000000, v0
	v_mul_f32_e32 v37, v23, v23
	v_mul_f32_e32 v38, v25, v25
	v_fmac_f32_e32 v37, v22, v22
	v_fmac_f32_e32 v38, v24, v24
	v_add_f32_e32 v37, v37, v38
	v_fmac_f32_e32 v21, 0xba000000, v0
	v_fmac_f32_e32 v19, 0xba000000, v0
	v_add_f32_e32 v36, v37, v36
	v_fmac_f32_e32 v20, 0xba000000, v0
	v_fmac_f32_e32 v18, 0xba000000, v0
	v_mul_f32_e32 v37, v19, v19
	v_mul_f32_e32 v38, v21, v21
	v_fmac_f32_e32 v37, v18, v18
	v_fmac_f32_e32 v38, v20, v20
	v_add_f32_e32 v37, v37, v38
	v_fmac_f32_e32 v17, 0xba000000, v0
	v_fmac_f32_e32 v15, 0xba000000, v0
	v_add_f32_e32 v36, v37, v36
	v_fmac_f32_e32 v16, 0xba000000, v0
	v_fmac_f32_e32 v14, 0xba000000, v0
	v_mul_f32_e32 v37, v15, v15
	v_mul_f32_e32 v38, v17, v17
	v_fmac_f32_e32 v37, v14, v14
	v_fmac_f32_e32 v38, v16, v16
	v_add_f32_e32 v37, v37, v38
	v_fmac_f32_e32 v13, 0xba000000, v0
	v_fmac_f32_e32 v11, 0xba000000, v0
	v_add_f32_e32 v36, v37, v36
	v_fmac_f32_e32 v12, 0xba000000, v0
	v_fmac_f32_e32 v10, 0xba000000, v0
	v_mul_f32_e32 v37, v11, v11
	v_mul_f32_e32 v38, v13, v13
	v_fmac_f32_e32 v37, v10, v10
	v_fmac_f32_e32 v38, v12, v12
	v_add_f32_e32 v37, v37, v38
	v_fmac_f32_e32 v9, 0xba000000, v0
	v_fmac_f32_e32 v7, 0xba000000, v0
	v_add_f32_e32 v36, v37, v36
	v_fmac_f32_e32 v8, 0xba000000, v0
	v_fmac_f32_e32 v6, 0xba000000, v0
	v_mul_f32_e32 v37, v7, v7
	v_mul_f32_e32 v38, v9, v9
	v_fmac_f32_e32 v37, v6, v6
	v_fmac_f32_e32 v38, v8, v8
	v_add_f32_e32 v37, v37, v38
	v_add_f32_e32 v50, v37, v36
	global_load_dwordx4 v[36:39], v[46:47], off offset:-4096
	global_load_dwordx4 v[130:133], v[46:47], off offset:-3072
	global_load_dwordx4 v[134:137], v[48:49], off offset:-3072
	global_load_dwordx4 v[138:141], v[46:47], off offset:-2048
	global_load_dwordx4 v[142:145], v[48:49], off offset:-2048
	global_load_dwordx4 v[146:149], v[46:47], off offset:-1024
	global_load_dwordx4 v[150:153], v[48:49], off offset:-1024
	global_load_dwordx4 v[154:157], v[46:47], off
	global_load_dwordx4 v[158:161], v[48:49], off
	global_load_dwordx4 v[162:165], v[46:47], off offset:1024
	global_load_dwordx4 v[166:169], v[48:49], off offset:1024
	global_load_dwordx4 v[170:173], v[46:47], off offset:2048
	global_load_dwordx4 v[174:177], v[48:49], off offset:2048
	global_load_dwordx4 v[178:181], v[46:47], off offset:3072
	global_load_dwordx4 v[182:185], v[48:49], off offset:3072
	v_fmac_f32_e32 v5, 0xba000000, v0
	v_fmac_f32_e32 v3, 0xba000000, v0
	v_fmac_f32_e32 v4, 0xba000000, v0
	v_fmac_f32_e32 v2, 0xba000000, v0
	v_mul_f32_e32 v0, v3, v3
	v_mul_f32_e32 v51, v5, v5
	v_fmac_f32_e32 v0, v2, v2
	v_fmac_f32_e32 v51, v4, v4
	v_add_f32_e32 v0, v0, v51
	v_add_f32_e32 v0, v0, v50
	ds_swizzle_b32 v50, v0 offset:swizzle(SWAP,1)
	s_waitcnt lgkmcnt(0)
	v_add_f32_e32 v0, v0, v50
	ds_swizzle_b32 v50, v0 offset:swizzle(SWAP,2)
	s_waitcnt lgkmcnt(0)
	v_add_f32_e32 v0, v0, v50
	ds_swizzle_b32 v50, v0 offset:swizzle(SWAP,4)
	s_waitcnt lgkmcnt(0)
	v_add_f32_e32 v0, v0, v50
	ds_swizzle_b32 v50, v0 offset:swizzle(SWAP,8)
	s_waitcnt lgkmcnt(0)
	v_add_f32_e32 v0, v0, v50
	ds_swizzle_b32 v50, v0 offset:swizzle(SWAP,16)
	s_waitcnt lgkmcnt(0)
	v_add_f32_e32 v0, v0, v50
	v_mov_b32_e32 v50, v0
	s_nop 1
	v_permlane32_swap_b32_e32 v0, v50
	v_add_f32_e32 v0, v0, v50
	v_fmamk_f32 v0, v0, 0x3a000000, v254
	v_mul_f32_e32 v50, 0x4f800000, v0
	v_cmp_gt_f32_e32 vcc, s55, v0
	s_waitcnt vmcnt(0)
	v_pk_add_f32 v[36:37], v[36:37], 1.0 op_sel_hi:[1,0]
	v_cndmask_b32_e32 v0, v0, v50, vcc
	v_sqrt_f32_e32 v50, v0
	s_nop 0
	v_add_u32_e32 v51, -1, v50
	v_fma_f32 v52, -v51, v50, v0
	v_cmp_ge_f32_e64 s[4:5], 0, v52
	v_add_u32_e32 v52, 1, v50
	s_nop 0
	v_cndmask_b32_e64 v51, v50, v51, s[4:5]
	v_fma_f32 v50, -v52, v50, v0
	v_cmp_lt_f32_e64 s[4:5], 0, v50
	s_nop 1
	v_cndmask_b32_e64 v50, v51, v52, s[4:5]
	v_mul_f32_e32 v51, 0x37800000, v50
	v_cndmask_b32_e32 v50, v50, v51, vcc
	v_mov_b32_e32 v51, 0x260
	v_cmp_class_f32_e32 vcc, v0, v51
	s_nop 1
	v_cndmask_b32_e32 v0, v50, v0, vcc
	v_div_scale_f32 v50, s[4:5], v0, v0, 1.0
	v_rcp_f32_e32 v51, v50
	s_mov_b64 s[4:5], 0x8000
	v_fma_f32 v52, -v50, v51, 1.0
	v_fmac_f32_e32 v51, v52, v51
	v_div_scale_f32 v52, vcc, 1.0, v0, 1.0
	v_mul_f32_e32 v53, v52, v51
	v_fma_f32 v54, -v50, v53, v52
	v_fmac_f32_e32 v53, v54, v51
	v_fma_f32 v50, -v50, v53, v52
	v_div_fmas_f32 v50, v50, v51, v53
	v_div_fixup_f32 v0, v50, v0, 1.0
	v_lshl_add_u64 v[52:53], v[34:35], 1, s[6:7]
	v_pk_mul_f32 v[30:31], v[30:31], v[0:1] op_sel_hi:[1,0]
	v_pk_mul_f32 v[32:33], v[32:33], v[0:1] op_sel_hi:[1,0]
	v_pk_add_f32 v[34:35], v[38:39], 1.0 op_sel_hi:[1,0]
	v_pk_fma_f32 v[30:31], v[36:37], v[30:31], v[40:41]
	v_pk_fma_f32 v[32:33], v[34:35], v[32:33], v[42:43]
	v_cvt_pk_bf16_f32 v30, v30, v31
	v_cvt_pk_bf16_f32 v31, v32, v33
	v_lshl_add_u64 v[50:51], v[44:45], 0, s[4:5]
	global_store_dwordx2 v[52:53], v[30:31], off
	v_pk_mul_f32 v[26:27], v[26:27], v[0:1] op_sel_hi:[1,0]
	v_pk_mul_f32 v[28:29], v[28:29], v[0:1] op_sel_hi:[1,0]
	v_pk_mul_f32 v[22:23], v[22:23], v[0:1] op_sel_hi:[1,0]
	v_pk_mul_f32 v[24:25], v[24:25], v[0:1] op_sel_hi:[1,0]
	v_pk_mul_f32 v[18:19], v[18:19], v[0:1] op_sel_hi:[1,0]
	v_pk_mul_f32 v[20:21], v[20:21], v[0:1] op_sel_hi:[1,0]
	v_pk_mul_f32 v[14:15], v[14:15], v[0:1] op_sel_hi:[1,0]
	v_pk_mul_f32 v[16:17], v[16:17], v[0:1] op_sel_hi:[1,0]
	v_pk_mul_f32 v[10:11], v[10:11], v[0:1] op_sel_hi:[1,0]
	v_pk_mul_f32 v[12:13], v[12:13], v[0:1] op_sel_hi:[1,0]
	v_pk_mul_f32 v[6:7], v[6:7], v[0:1] op_sel_hi:[1,0]
	v_pk_mul_f32 v[8:9], v[8:9], v[0:1] op_sel_hi:[1,0]
	v_pk_mul_f32 v[2:3], v[2:3], v[0:1] op_sel_hi:[1,0]
	v_pk_mul_f32 v[4:5], v[4:5], v[0:1] op_sel_hi:[1,0]
	v_readlane_b32 s4, v255, 30
	v_readlane_b32 s5, v255, 31
	s_add_u32 s8, s8, s4
	s_addc_u32 s9, s9, s5
	s_nop 0
	v_readlane_b32 s4, v255, 38
	v_readlane_b32 s5, v255, 39
	s_add_u32 s6, s6, s4
	s_addc_u32 s7, s7, s5
	s_cmp_ge_i32 s10, s94
	v_pk_add_f32 v[132:133], v[132:133], 1.0 op_sel_hi:[1,0]
	v_pk_add_f32 v[130:131], v[130:131], 1.0 op_sel_hi:[1,0]
	v_pk_fma_f32 v[28:29], v[132:133], v[28:29], v[136:137]
	v_pk_fma_f32 v[26:27], v[130:131], v[26:27], v[134:135]
	s_nop 0
	v_cvt_pk_bf16_f32 v26, v26, v27
	v_cvt_pk_bf16_f32 v27, v28, v29
	global_store_dwordx2 v[52:53], v[26:27], off offset:512
	v_pk_add_f32 v[140:141], v[140:141], 1.0 op_sel_hi:[1,0]
	v_pk_add_f32 v[138:139], v[138:139], 1.0 op_sel_hi:[1,0]
	v_pk_fma_f32 v[24:25], v[140:141], v[24:25], v[144:145]
	v_pk_fma_f32 v[22:23], v[138:139], v[22:23], v[142:143]
	s_nop 0
	v_cvt_pk_bf16_f32 v22, v22, v23
	v_cvt_pk_bf16_f32 v23, v24, v25
	global_store_dwordx2 v[52:53], v[22:23], off offset:1024
	v_pk_add_f32 v[148:149], v[148:149], 1.0 op_sel_hi:[1,0]
	v_pk_add_f32 v[146:147], v[146:147], 1.0 op_sel_hi:[1,0]
	v_pk_fma_f32 v[20:21], v[148:149], v[20:21], v[152:153]
	v_pk_fma_f32 v[18:19], v[146:147], v[18:19], v[150:151]
	s_nop 0
	v_cvt_pk_bf16_f32 v18, v18, v19
	v_cvt_pk_bf16_f32 v19, v20, v21
	global_store_dwordx2 v[52:53], v[18:19], off offset:1536
	v_pk_add_f32 v[156:157], v[156:157], 1.0 op_sel_hi:[1,0]
	v_pk_add_f32 v[154:155], v[154:155], 1.0 op_sel_hi:[1,0]
	v_pk_fma_f32 v[16:17], v[156:157], v[16:17], v[160:161]
	v_pk_fma_f32 v[14:15], v[154:155], v[14:15], v[158:159]
	s_nop 0
	v_cvt_pk_bf16_f32 v14, v14, v15
	v_cvt_pk_bf16_f32 v15, v16, v17
	global_store_dwordx2 v[52:53], v[14:15], off offset:2048
	v_pk_add_f32 v[164:165], v[164:165], 1.0 op_sel_hi:[1,0]
	v_pk_add_f32 v[162:163], v[162:163], 1.0 op_sel_hi:[1,0]
	v_pk_fma_f32 v[12:13], v[164:165], v[12:13], v[168:169]
	v_pk_fma_f32 v[10:11], v[162:163], v[10:11], v[166:167]
	s_nop 0
	v_cvt_pk_bf16_f32 v10, v10, v11
	v_cvt_pk_bf16_f32 v11, v12, v13
	global_store_dwordx2 v[52:53], v[10:11], off offset:2560
	v_pk_add_f32 v[172:173], v[172:173], 1.0 op_sel_hi:[1,0]
	v_pk_add_f32 v[170:171], v[170:171], 1.0 op_sel_hi:[1,0]
	v_pk_fma_f32 v[8:9], v[172:173], v[8:9], v[176:177]
	v_pk_fma_f32 v[6:7], v[170:171], v[6:7], v[174:175]
	s_nop 0
	v_cvt_pk_bf16_f32 v6, v6, v7
	v_cvt_pk_bf16_f32 v7, v8, v9
	global_store_dwordx2 v[52:53], v[6:7], off offset:3072
	v_pk_add_f32 v[180:181], v[180:181], 1.0 op_sel_hi:[1,0]
	v_pk_add_f32 v[178:179], v[178:179], 1.0 op_sel_hi:[1,0]
	v_pk_fma_f32 v[4:5], v[180:181], v[4:5], v[184:185]
	v_pk_fma_f32 v[2:3], v[178:179], v[2:3], v[182:183]
	s_nop 0
	v_cvt_pk_bf16_f32 v2, v2, v3
	v_cvt_pk_bf16_f32 v3, v4, v5
	global_store_dwordx2 v[52:53], v[2:3], off offset:3584
	s_cbranch_scc1 .LBB0_1567
